# adds: K tile LDS swizzle over 4 row bits in the DK=128 attention path (removes 2-way bank conflict of QK^T reads)
# speedup vs baseline: 1.0021x; 1.0021x over previous
.LBB0_586:
	v_mov_b32_e32 v40, v0
	s_add_i32 s18, s80, -1
	v_ashrrev_i32_e32 v178, 6, v40
	v_and_b32_e32 v165, 31, v40
	v_lshlrev_b32_e32 v1, 5, v178
	v_or_b32_e32 v2, v1, v165
	v_add_u32_e32 v179, s82, v2
	v_min_i32_e32 v2, s18, v179
	v_ashrrev_i32_e32 v5, 31, v2
	v_mad_u64_u32 v[2:3], s[18:19], v2, s26, 0
	v_mov_b32_e32 v4, v3
	v_mad_u64_u32 v[4:5], s[18:19], v5, s26, v[4:5]
	v_bfe_u32 v164, v40, 5, 1
	v_mov_b32_e32 v3, v4
	v_lshl_add_u64 v[2:3], v[2:3], 1, s[4:5]
	v_lshlrev_b32_e32 v146, 4, v164
	v_mov_b32_e32 v147, v167
	v_lshl_add_u64 v[2:3], v[2:3], 0, v[146:147]
	global_load_dwordx4 v[142:145], v[2:3], off
	global_load_dwordx4 v[138:141], v[2:3], off offset:32
	global_load_dwordx4 v[134:137], v[2:3], off offset:64
	global_load_dwordx4 v[130:133], v[2:3], off offset:96
	global_load_dwordx4 v[126:129], v[2:3], off offset:128
	global_load_dwordx4 v[122:125], v[2:3], off offset:160
	global_load_dwordx4 v[118:121], v[2:3], off offset:192
	global_load_dwordx4 v[114:117], v[2:3], off offset:224
	v_ashrrev_i32_e32 v2, 4, v40
	v_and_b32_e32 v5, 0xfffff0, v2
	v_lshlrev_b32_e32 v6, 1, v2
	v_and_or_b32 v5, v6, 8, v5
	v_lshrrev_b32_e32 v6, 1, v2
	v_and_b32_e32 v7, 3, v2
	v_and_or_b32 v6, v6, 4, v7
	v_lshlrev_b32_e32 v18, 6, v6
	v_add_u32_e32 v6, 32, v2
	v_and_b32_e32 v7, 0xfffff0, v6
	v_lshlrev_b32_e32 v6, 1, v6
	v_lshlrev_b32_e32 v3, 3, v40
	v_and_or_b32 v6, v6, 8, v7
	v_and_b32_e32 v4, 0x78, v3
	v_lshrrev_b32_e32 v5, 1, v5
	v_bfe_u32 v3, v3, 5, 2
	v_lshrrev_b32_e32 v6, 1, v6
	v_or_b32_e32 v5, v5, v3
	v_or_b32_e32 v3, v6, v3
	v_mul_lo_u32 v2, v2, s26
	v_lshlrev_b32_e32 v19, 9, v3
	v_or_b32_e32 v3, v2, v4
	v_lshl_add_u32 v2, s26, 5, v2
	v_or_b32_e32 v2, v2, v4
	v_ashrrev_i32_e32 v4, 31, v40
	v_lshrrev_b32_e32 v4, 28, v4
	v_add_u32_e32 v4, v40, v4
	s_lshl_b32 s4, s26, 1
	v_ashrrev_i32_e32 v6, 4, v4
	v_and_b32_e32 v4, -16, v4
	v_sub_u32_e32 v4, v40, v4
	v_mul_lo_u32 v7, v6, s4
	v_lshl_add_u32 v34, v4, 4, v7
	v_lshlrev_b32_e32 v7, 8, v6
	v_bitop3_b32 v4, v6, v4, 15 bitop3:0x6c
	v_lshl_add_u32 v20, v4, 4, v7
	v_add_u32_e32 v4, 0x200, v40
	v_ashrrev_i32_e32 v6, 31, v4
	v_lshrrev_b32_e32 v6, 28, v6
	v_add_u32_e32 v6, v4, v6
	v_ashrrev_i32_e32 v7, 4, v6
	v_and_b32_e32 v6, -16, v6
	v_sub_u32_e32 v4, v4, v6
	v_mul_lo_u32 v6, v7, s4
	s_mul_hi_u32 s5, s20, s26
	s_mul_i32 s4, s20, s26
	s_lshl_b64 s[4:5], s[4:5], 7
	s_add_u32 s18, s8, s4
	v_lshlrev_b32_e32 v147, 4, v40
	s_addc_u32 s19, s9, s5
	v_lshlrev_b32_e32 v5, 9, v5
	v_lshl_add_u32 v36, v4, 4, v6
	v_lshlrev_b32_e32 v6, 8, v7
	v_bitop3_b32 v4, v7, v4, 15 bitop3:0x6c
	v_and_b32_e32 v22, 48, v147
	v_lshlrev_b32_e32 v166, 1, v3
	s_add_u32 s4, s6, s4
	v_lshl_add_u32 v21, v4, 4, v6
	v_or3_b32 v23, v5, v18, v22
	v_lshlrev_b32_e32 v38, 1, v2
	s_addc_u32 s5, s7, s5
	global_load_dwordx4 v[2:5], v166, s[18:19]
	global_load_dwordx4 v[6:9], v38, s[18:19]
	global_load_dwordx4 v[10:13], v34, s[4:5]
	global_load_dwordx4 v[14:17], v36, s[4:5]
	s_add_i32 s100, s20, 1
	s_mul_hi_u32 s101, s100, s26
	s_mul_i32 s100, s100, s26
	s_lshl_b64 s[100:101], s[100:101], 7
	s_add_u32 s100, s8, s100
	s_addc_u32 s101, s9, s101
	global_load_dwordx4 v[66:69], v166, s[100:101]
	global_load_dwordx4 v[70:73], v38, s[100:101]
	s_sub_u32 s100, s100, s8
	s_subb_u32 s101, s101, s9
	s_add_u32 s100, s100, s6
	s_addc_u32 s101, s101, s7
	global_load_dwordx4 v[74:77], v34, s[100:101]
	global_load_dwordx4 v[78:81], v36, s[100:101]
	v_add_u32_e32 v208, 0, v23
	s_movk_i32 s4, 0xf0
	v_or3_b32 v18, v19, v18, v22
	v_lshl_add_u32 v37, v165, 8, 0
	v_add_u32_e32 v209, 0, v18
	v_add_u32_e32 v210, 0, v20
	v_add_u32_e32 v211, 0, v21
	v_and_b32_e32 v35, 0xf0, v147
	v_bitop3_b32 v39, v146, v35, 32 bitop3:0x36
	v_add_u32_e32 v186, v37, v39
	v_bitop3_b32 v39, v146, v35, 64 bitop3:0x36
	v_add_u32_e32 v187, v37, v39
	s_cmp_lt_u32 s84, s80
	s_cselect_b64 s[18:19], -1, 0
	s_cmp_ge_u32 s84, s80
	s_waitcnt vmcnt(7)
	ds_write_b128 v208, v[2:5]
	v_bitop3_b32 v2, v146, v147, s4 bitop3:0x78
	v_add_u32_e32 v185, v37, v2
	s_waitcnt vmcnt(6)
	ds_write_b128 v209, v[6:9]
	s_waitcnt vmcnt(5)
	ds_write_b128 v210, v[10:13] offset:32768
	s_waitcnt vmcnt(4)
	ds_write_b128 v211, v[14:17] offset:32768
	s_waitcnt lgkmcnt(0)
	s_barrier
	ds_read_b128 v[2:5], v185 offset:32768
	ds_read_b128 v[6:9], v185 offset:40960
	s_waitcnt lgkmcnt(1)
	v_mfma_f32_32x32x16_bf16 v[18:33], v[2:5], v[142:145], 0
	ds_read_b128 v[42:45], v186 offset:32768
	ds_read_b128 v[46:49], v186 offset:40960
	s_movk_i32 s4, 0x60
	v_bitop3_b32 v39, v146, v35, s4 bitop3:0x36
	v_add_u32_e32 v188, v37, v39
	s_movk_i32 s4, 0x80
	v_bitop3_b32 v39, v146, v35, s4 bitop3:0x36
	v_add_u32_e32 v189, v37, v39
	s_waitcnt lgkmcnt(2)
	v_mfma_f32_32x32x16_bf16 v[2:17], v[6:9], v[142:145], 0
	s_movk_i32 s4, 0xa0
	v_bitop3_b32 v39, v146, v35, s4 bitop3:0x36
	v_add_u32_e32 v205, v37, v39
	s_movk_i32 s4, 0xc0
	v_bitop3_b32 v39, v146, v35, s4 bitop3:0x36
	v_add_u32_e32 v206, v37, v39
	s_movk_i32 s4, 0xe0
	s_waitcnt lgkmcnt(1)
	v_mfma_f32_32x32x16_bf16 v[18:33], v[42:45], v[138:141], v[18:33]
	v_bitop3_b32 v35, v146, v35, s4 bitop3:0x36
	v_add_u32_e32 v207, v37, v35
	s_waitcnt lgkmcnt(0)
	v_mfma_f32_32x32x16_bf16 v[2:17], v[46:49], v[138:141], v[2:17]
	ds_read_b128 v[42:45], v187 offset:32768
	ds_read_b128 v[46:49], v187 offset:40960
	s_waitcnt lgkmcnt(1)
	v_mfma_f32_32x32x16_bf16 v[18:33], v[42:45], v[134:137], v[18:33]
	s_waitcnt lgkmcnt(0)
	v_mfma_f32_32x32x16_bf16 v[2:17], v[46:49], v[134:137], v[2:17]
	ds_read_b128 v[42:45], v188 offset:32768
	ds_read_b128 v[46:49], v188 offset:40960
	s_waitcnt lgkmcnt(1)
	v_mfma_f32_32x32x16_bf16 v[18:33], v[42:45], v[130:133], v[18:33]
	s_waitcnt lgkmcnt(0)
	v_mfma_f32_32x32x16_bf16 v[2:17], v[46:49], v[130:133], v[2:17]
	ds_read_b128 v[42:45], v189 offset:32768
	ds_read_b128 v[46:49], v189 offset:40960
	s_waitcnt lgkmcnt(1)
	v_mfma_f32_32x32x16_bf16 v[18:33], v[42:45], v[126:129], v[18:33]
	s_waitcnt lgkmcnt(0)
	v_mfma_f32_32x32x16_bf16 v[2:17], v[46:49], v[126:129], v[2:17]
	ds_read_b128 v[42:45], v205 offset:32768
	ds_read_b128 v[46:49], v205 offset:40960
	s_waitcnt lgkmcnt(1)
	v_mfma_f32_32x32x16_bf16 v[18:33], v[42:45], v[122:125], v[18:33]
	s_waitcnt lgkmcnt(0)
	v_mfma_f32_32x32x16_bf16 v[2:17], v[46:49], v[122:125], v[2:17]
	ds_read_b128 v[42:45], v206 offset:32768
	ds_read_b128 v[46:49], v206 offset:40960
	s_waitcnt lgkmcnt(1)
	v_mfma_f32_32x32x16_bf16 v[18:33], v[42:45], v[118:121], v[18:33]
	s_waitcnt lgkmcnt(0)
	v_mfma_f32_32x32x16_bf16 v[2:17], v[46:49], v[118:121], v[2:17]
	ds_read_b128 v[42:45], v207 offset:32768
	ds_read_b128 v[46:49], v207 offset:40960
	s_waitcnt lgkmcnt(1)
	v_mfma_f32_32x32x16_bf16 v[18:33], v[42:45], v[114:117], v[18:33]
	s_waitcnt lgkmcnt(0)
	v_mfma_f32_32x32x16_bf16 v[2:17], v[46:49], v[114:117], v[2:17]
	s_cbranch_scc1 .LBB0_588
	s_lshl_b32 s4, s20, 6
	v_lshl_or_b32 v35, v164, 2, s4
	s_sub_i32 s21, 0, s84
	v_sub_u32_e32 v37, v179, v35
	v_cmp_lt_i32_e32 vcc, s84, v37
	v_cmp_gt_i32_e64 s[4:5], s21, v37
	s_or_b64 vcc, vcc, s[4:5]
	v_subrev_u32_e32 v37, 32, v37
	s_nop 0
	v_cndmask_b32_e32 v18, v18, v203, vcc
	v_cmp_lt_i32_e32 vcc, s84, v37
	v_cmp_gt_i32_e64 s[4:5], s21, v37
	s_or_b64 vcc, vcc, s[4:5]
	v_xad_u32 v37, v35, -1, v179
	v_cndmask_b32_e32 v2, v2, v203, vcc
	v_cmp_lt_i32_e32 vcc, s84, v37
	v_cmp_gt_i32_e64 s[4:5], s21, v37
	s_or_b64 vcc, vcc, s[4:5]
	v_subrev_u32_e32 v37, 32, v37
	v_cndmask_b32_e32 v19, v19, v203, vcc
	v_cmp_lt_i32_e32 vcc, s84, v37
	v_cmp_gt_i32_e64 s[4:5], s21, v37
	v_or_b32_e32 v37, 2, v35
	s_or_b64 vcc, vcc, s[4:5]
	v_sub_u32_e32 v37, v179, v37
	v_cndmask_b32_e32 v3, v3, v203, vcc
	v_cmp_lt_i32_e32 vcc, s84, v37
	v_cmp_gt_i32_e64 s[4:5], s21, v37
	s_or_b64 vcc, vcc, s[4:5]
	v_subrev_u32_e32 v37, 32, v37
	v_cndmask_b32_e32 v20, v20, v203, vcc
	v_cmp_lt_i32_e32 vcc, s84, v37
	v_cmp_gt_i32_e64 s[4:5], s21, v37
	v_or_b32_e32 v37, 3, v35
	s_or_b64 vcc, vcc, s[4:5]
	v_sub_u32_e32 v37, v179, v37
	v_cndmask_b32_e32 v4, v4, v203, vcc
	v_cmp_lt_i32_e32 vcc, s84, v37
	v_cmp_gt_i32_e64 s[4:5], s21, v37
	s_or_b64 vcc, vcc, s[4:5]
	v_subrev_u32_e32 v37, 32, v37
	v_cndmask_b32_e32 v21, v21, v203, vcc
	v_cmp_lt_i32_e32 vcc, s84, v37
	v_cmp_gt_i32_e64 s[4:5], s21, v37
	v_or_b32_e32 v37, 8, v35
	s_or_b64 vcc, vcc, s[4:5]
	v_sub_u32_e32 v37, v179, v37
	v_cndmask_b32_e32 v5, v5, v203, vcc
	v_cmp_lt_i32_e32 vcc, s84, v37
	v_cmp_gt_i32_e64 s[4:5], s21, v37
	s_or_b64 vcc, vcc, s[4:5]
	v_subrev_u32_e32 v37, 32, v37
	v_cndmask_b32_e32 v22, v22, v203, vcc
	v_cmp_lt_i32_e32 vcc, s84, v37
	v_cmp_gt_i32_e64 s[4:5], s21, v37
	v_or_b32_e32 v37, 9, v35
	s_or_b64 vcc, vcc, s[4:5]
	v_sub_u32_e32 v37, v179, v37
	v_cndmask_b32_e32 v6, v6, v203, vcc
	v_cmp_lt_i32_e32 vcc, s84, v37
	v_cmp_gt_i32_e64 s[4:5], s21, v37
	s_or_b64 vcc, vcc, s[4:5]
	v_subrev_u32_e32 v37, 32, v37
	v_cndmask_b32_e32 v23, v23, v203, vcc
	v_cmp_lt_i32_e32 vcc, s84, v37
	v_cmp_gt_i32_e64 s[4:5], s21, v37
	v_or_b32_e32 v37, 10, v35
	s_or_b64 vcc, vcc, s[4:5]
	v_sub_u32_e32 v37, v179, v37
	v_cndmask_b32_e32 v7, v7, v203, vcc
	v_cmp_lt_i32_e32 vcc, s84, v37
	v_cmp_gt_i32_e64 s[4:5], s21, v37
	s_or_b64 vcc, vcc, s[4:5]
	v_subrev_u32_e32 v37, 32, v37
	v_cndmask_b32_e32 v24, v24, v203, vcc
	v_cmp_lt_i32_e32 vcc, s84, v37
	v_cmp_gt_i32_e64 s[4:5], s21, v37
	v_or_b32_e32 v37, 11, v35
	s_or_b64 vcc, vcc, s[4:5]
	v_sub_u32_e32 v37, v179, v37
	v_cndmask_b32_e32 v8, v8, v203, vcc
	v_cmp_lt_i32_e32 vcc, s84, v37
	v_cmp_gt_i32_e64 s[4:5], s21, v37
	s_or_b64 vcc, vcc, s[4:5]
	v_subrev_u32_e32 v37, 32, v37
	v_cndmask_b32_e32 v25, v25, v203, vcc
	v_cmp_lt_i32_e32 vcc, s84, v37
	v_cmp_gt_i32_e64 s[4:5], s21, v37
	v_or_b32_e32 v37, 16, v35
	s_or_b64 vcc, vcc, s[4:5]
	v_sub_u32_e32 v37, v179, v37
	v_cndmask_b32_e32 v9, v9, v203, vcc
	v_cmp_lt_i32_e32 vcc, s84, v37
	v_cmp_gt_i32_e64 s[4:5], s21, v37
	s_or_b64 vcc, vcc, s[4:5]
	v_subrev_u32_e32 v37, 32, v37
	v_cndmask_b32_e32 v26, v26, v203, vcc
	v_cmp_lt_i32_e32 vcc, s84, v37
	v_cmp_gt_i32_e64 s[4:5], s21, v37
	v_or_b32_e32 v37, 17, v35
	s_or_b64 vcc, vcc, s[4:5]
	v_sub_u32_e32 v37, v179, v37
	v_cndmask_b32_e32 v10, v10, v203, vcc
	v_cmp_lt_i32_e32 vcc, s84, v37
	v_cmp_gt_i32_e64 s[4:5], s21, v37
	s_or_b64 vcc, vcc, s[4:5]
	v_subrev_u32_e32 v37, 32, v37
	v_cndmask_b32_e32 v27, v27, v203, vcc
	v_cmp_lt_i32_e32 vcc, s84, v37
	v_cmp_gt_i32_e64 s[4:5], s21, v37
	v_or_b32_e32 v37, 18, v35
	s_or_b64 vcc, vcc, s[4:5]
	v_sub_u32_e32 v37, v179, v37
	v_cndmask_b32_e32 v11, v11, v203, vcc
	v_cmp_lt_i32_e32 vcc, s84, v37
	v_cmp_gt_i32_e64 s[4:5], s21, v37
	s_or_b64 vcc, vcc, s[4:5]
	v_subrev_u32_e32 v37, 32, v37
	v_cndmask_b32_e32 v28, v28, v203, vcc
	v_cmp_lt_i32_e32 vcc, s84, v37
	v_cmp_gt_i32_e64 s[4:5], s21, v37
	v_or_b32_e32 v37, 19, v35
	s_or_b64 vcc, vcc, s[4:5]
	v_sub_u32_e32 v37, v179, v37
	v_cndmask_b32_e32 v12, v12, v203, vcc
	v_cmp_lt_i32_e32 vcc, s84, v37
	v_cmp_gt_i32_e64 s[4:5], s21, v37
	s_or_b64 vcc, vcc, s[4:5]
	v_subrev_u32_e32 v37, 32, v37
	v_cndmask_b32_e32 v29, v29, v203, vcc
	v_cmp_lt_i32_e32 vcc, s84, v37
	v_cmp_gt_i32_e64 s[4:5], s21, v37
	v_or_b32_e32 v37, 24, v35
	s_or_b64 vcc, vcc, s[4:5]
	v_sub_u32_e32 v37, v179, v37
	v_cndmask_b32_e32 v13, v13, v203, vcc
	v_cmp_lt_i32_e32 vcc, s84, v37
	v_cmp_gt_i32_e64 s[4:5], s21, v37
	s_or_b64 vcc, vcc, s[4:5]
	v_subrev_u32_e32 v37, 32, v37
	v_cndmask_b32_e32 v30, v30, v203, vcc
	v_cmp_lt_i32_e32 vcc, s84, v37
	v_cmp_gt_i32_e64 s[4:5], s21, v37
	v_or_b32_e32 v37, 25, v35
	s_or_b64 vcc, vcc, s[4:5]
	v_sub_u32_e32 v37, v179, v37
	v_cndmask_b32_e32 v14, v14, v203, vcc
	v_cmp_lt_i32_e32 vcc, s84, v37
	v_cmp_gt_i32_e64 s[4:5], s21, v37
	s_or_b64 vcc, vcc, s[4:5]
	v_subrev_u32_e32 v37, 32, v37
	v_cndmask_b32_e32 v31, v31, v203, vcc
	v_cmp_lt_i32_e32 vcc, s84, v37
	v_cmp_gt_i32_e64 s[4:5], s21, v37
	v_or_b32_e32 v37, 26, v35
	s_or_b64 vcc, vcc, s[4:5]
	v_sub_u32_e32 v37, v179, v37
	v_cndmask_b32_e32 v15, v15, v203, vcc
	v_cmp_lt_i32_e32 vcc, s84, v37
	v_cmp_gt_i32_e64 s[4:5], s21, v37
	s_or_b64 vcc, vcc, s[4:5]
	v_subrev_u32_e32 v37, 32, v37
	v_cndmask_b32_e32 v32, v32, v203, vcc
	v_cmp_lt_i32_e32 vcc, s84, v37
	v_cmp_gt_i32_e64 s[4:5], s21, v37
	v_or_b32_e32 v35, 27, v35
	s_or_b64 vcc, vcc, s[4:5]
	v_sub_u32_e32 v35, v179, v35
	v_cndmask_b32_e32 v16, v16, v203, vcc
	v_cmp_lt_i32_e32 vcc, s84, v35
	v_cmp_gt_i32_e64 s[4:5], s21, v35
	s_or_b64 vcc, vcc, s[4:5]
	v_subrev_u32_e32 v35, 32, v35
	v_cndmask_b32_e32 v33, v33, v203, vcc
	v_cmp_lt_i32_e32 vcc, s84, v35
	v_cmp_gt_i32_e64 s[4:5], s21, v35
	s_or_b64 vcc, vcc, s[4:5]
	v_cndmask_b32_e32 v17, v17, v203, vcc
